# out-proj f32-source residual epilogue: residual loads issued in three batches instead of 16 serial load-wait-store round trips
# speedup vs baseline: 1.0085x; 1.0011x over previous
;     DI void operator()(const f32x4 (&acc)[2][2][4][2], const Unit& u, int wr, int wc, int fr_, int fq_) const {
;     ...
;         const int b = u.pm / 33, tt = u.pm % 33;
;         const size_t roff = ((size_t)b * SEQ + (size_t)(tt - 1) * 256) * DM;
;         const float* gp = gate + (size_t)b * 12288;
;         const int col0 = u.pn * BM + wc * 32 + 8 * fq;
;         f32x4 gq[2][2];
; #pragma unroll
;         for (int bj = 0; bj < 2; ++bj) { gq[bj][0] = *(const f32x4*)(gp + col0 + bj * HALF); gq[bj][1] = *(const f32x4*)(gp + col0 + bj * HALF + 4); }
;         if (sb) {
; #pragma unroll
;             for (int ai = 0; ai < 2; ++ai) {
;                 u32x4 pre[4][2];
; #pragma unroll
;                 for (int m = 0; m < 4; ++m) { const size_t off = roff + (size_t)(ai * HALF + wr * 64 + m * 16 + fr) * DM + col0;
; #pragma unroll
;                     for (int bj = 0; bj < 2; ++bj) pre[m][bj] = *(const u32x4*)((const bf16_t*)src + off + bj * HALF); }
; #pragma unroll
;                 for (int m = 0; m < 4; ++m) { const size_t off = roff + (size_t)(ai * HALF + wr * 64 + m * 16 + fr) * DM + col0;
; #pragma unroll
;                     for (int bj = 0; bj < 2; ++bj) { const int cc = bj * HALF; const u32x4 w = pre[m][bj];
;                         const f32x4 s0 = (f32x4){bf2f(w.x & 0xffff), bf2f(w.x >> 16), bf2f(w.y & 0xffff), bf2f(w.y >> 16)}, s1 = (f32x4){bf2f(w.z & 0xffff), bf2f(w.z >> 16), bf2f(w.w & 0xffff), bf2f(w.w >> 16)};
;                         const f32x4 o0 = s0 + gq[bj][0] * acc[ai][bj][m][0], o1 = s1 + gq[bj][1] * acc[ai][bj][m][1];
;                         if (db) { u32x4 o; o.x = cvt_pk_bf16(o0[0], o0[1]); o.y = cvt_pk_bf16(o0[2], o0[3]); o.z = cvt_pk_bf16(o1[0], o1[1]); o.w = cvt_pk_bf16(o1[2], o1[3]); *(u32x4*)((bf16_t*)dst + off + cc) = o; }
;                         else { *(f32x4*)((float*)dst + off + cc) = o0; *(f32x4*)((float*)dst + off + cc + 4) = o1; } } }
;                 asm volatile("" ::: "memory"); }
;         } else {
; #pragma unroll
;             for (int ai = 0; ai < 2; ++ai)
; #pragma unroll
;                 for (int m = 0; m < 4; ++m) { const size_t off = roff + (size_t)(ai * HALF + wr * 64 + m * 16 + fr) * DM + col0;
; #pragma unroll
;                     for (int bj = 0; bj < 2; ++bj) { const int cc = bj * HALF;
.LBB0_750:
	s_nop 0
	v_lshlrev_b64 v[220:221], 11, v[192:193]
	v_lshl_add_u64 v[220:221], v[174:175], 0, v[220:221]
	v_lshl_add_u64 v[212:213], v[220:221], 2, s[4:5]
	v_lshl_add_u64 v[214:215], v[220:221], 1, s[6:7]
	global_load_dwordx4 v[144:147], v[212:213], off
	global_load_dwordx4 v[148:151], v[212:213], off offset:16
	global_load_dwordx4 v[152:155], v[212:213], off offset:512
	global_load_dwordx4 v[156:159], v[212:213], off offset:528
	v_lshlrev_b64 v[220:221], 11, v[190:191]
	v_lshl_add_u64 v[220:221], v[174:175], 0, v[220:221]
	v_lshl_add_u64 v[216:217], v[220:221], 2, s[4:5]
	v_lshl_add_u64 v[218:219], v[220:221], 1, s[6:7]
	global_load_dwordx4 v[160:163], v[216:217], off
	global_load_dwordx4 v[194:197], v[216:217], off offset:16
	global_load_dwordx4 v[198:201], v[216:217], off offset:512
	global_load_dwordx4 v[208:211], v[216:217], off offset:528
	s_waitcnt vmcnt(6)
	v_pk_fma_f32 v[120:121], v[120:121], v[140:141], v[144:145]
	v_pk_fma_f32 v[122:123], v[122:123], v[142:143], v[146:147]
	v_pk_fma_f32 v[124:125], v[124:125], v[136:137], v[148:149]
	v_pk_fma_f32 v[126:127], v[126:127], v[138:139], v[150:151]
	v_cvt_pk_bf16_f32 v144, v120, v121
	v_cvt_pk_bf16_f32 v145, v122, v123
	v_cvt_pk_bf16_f32 v146, v124, v125
	v_cvt_pk_bf16_f32 v147, v126, v127
	global_store_dwordx4 v[214:215], v[144:147], off
	s_waitcnt vmcnt(5)
	v_pk_fma_f32 v[116:117], v[116:117], v[132:133], v[152:153]
	v_pk_fma_f32 v[118:119], v[118:119], v[134:135], v[154:155]
	v_pk_fma_f32 v[112:113], v[112:113], v[128:129], v[156:157]
	v_pk_fma_f32 v[114:115], v[114:115], v[130:131], v[158:159]
	v_cvt_pk_bf16_f32 v152, v116, v117
	v_cvt_pk_bf16_f32 v153, v118, v119
	v_cvt_pk_bf16_f32 v154, v112, v113
	v_cvt_pk_bf16_f32 v155, v114, v115
	global_store_dwordx4 v[214:215], v[152:155], off offset:256
	s_waitcnt vmcnt(4)
	v_pk_fma_f32 v[108:109], v[108:109], v[140:141], v[160:161]
	v_pk_fma_f32 v[110:111], v[110:111], v[142:143], v[162:163]
	v_pk_fma_f32 v[104:105], v[104:105], v[136:137], v[194:195]
	v_pk_fma_f32 v[106:107], v[106:107], v[138:139], v[196:197]
	v_cvt_pk_bf16_f32 v160, v108, v109
	v_cvt_pk_bf16_f32 v161, v110, v111
	v_cvt_pk_bf16_f32 v162, v104, v105
	v_cvt_pk_bf16_f32 v163, v106, v107
	global_store_dwordx4 v[218:219], v[160:163], off
	s_waitcnt vmcnt(3)
	v_pk_fma_f32 v[100:101], v[100:101], v[132:133], v[198:199]
	v_pk_fma_f32 v[102:103], v[102:103], v[134:135], v[200:201]
	v_pk_fma_f32 v[96:97], v[96:97], v[128:129], v[208:209]
	v_pk_fma_f32 v[98:99], v[98:99], v[130:131], v[210:211]
	v_cvt_pk_bf16_f32 v198, v100, v101
	v_cvt_pk_bf16_f32 v199, v102, v103
	v_cvt_pk_bf16_f32 v200, v96, v97
	v_cvt_pk_bf16_f32 v201, v98, v99
	global_store_dwordx4 v[218:219], v[198:201], off offset:256
	v_lshlrev_b64 v[220:221], 11, v[188:189]
	v_lshl_add_u64 v[220:221], v[174:175], 0, v[220:221]
	v_lshl_add_u64 v[212:213], v[220:221], 2, s[4:5]
	v_lshl_add_u64 v[214:215], v[220:221], 1, s[6:7]
	global_load_dwordx4 v[96:99], v[212:213], off
	global_load_dwordx4 v[100:103], v[212:213], off offset:16
	global_load_dwordx4 v[104:107], v[212:213], off offset:512
	global_load_dwordx4 v[108:111], v[212:213], off offset:528
	v_lshlrev_b64 v[220:221], 11, v[186:187]
	v_lshl_add_u64 v[220:221], v[174:175], 0, v[220:221]
	v_lshl_add_u64 v[216:217], v[220:221], 2, s[4:5]
	v_lshl_add_u64 v[218:219], v[220:221], 1, s[6:7]
	global_load_dwordx4 v[112:115], v[216:217], off
	global_load_dwordx4 v[116:119], v[216:217], off offset:16
	global_load_dwordx4 v[120:123], v[216:217], off offset:512
	global_load_dwordx4 v[124:127], v[216:217], off offset:528
	v_lshlrev_b64 v[220:221], 11, v[184:185]
	v_lshl_add_u64 v[220:221], v[174:175], 0, v[220:221]
	v_lshl_add_u64 v[202:203], v[220:221], 2, s[4:5]
	v_lshl_add_u64 v[228:229], v[220:221], 1, s[6:7]
	global_load_dwordx4 v[144:147], v[202:203], off
	global_load_dwordx4 v[148:151], v[202:203], off offset:16
	global_load_dwordx4 v[152:155], v[202:203], off offset:512
	global_load_dwordx4 v[156:159], v[202:203], off offset:528
	v_lshlrev_b64 v[220:221], 11, v[182:183]
	v_lshl_add_u64 v[220:221], v[174:175], 0, v[220:221]
	v_lshl_add_u64 v[230:231], v[220:221], 2, s[4:5]
	v_lshl_add_u64 v[232:233], v[220:221], 1, s[6:7]
	global_load_dwordx4 v[160:163], v[230:231], off
	global_load_dwordx4 v[194:197], v[230:231], off offset:16
	global_load_dwordx4 v[198:201], v[230:231], off offset:512
	global_load_dwordx4 v[208:211], v[230:231], off offset:528
	s_waitcnt vmcnt(14)
	v_pk_fma_f32 v[92:93], v[92:93], v[140:141], v[96:97]
	v_pk_fma_f32 v[94:95], v[94:95], v[142:143], v[98:99]
	v_pk_fma_f32 v[88:89], v[88:89], v[136:137], v[100:101]
	v_pk_fma_f32 v[90:91], v[90:91], v[138:139], v[102:103]
	v_cvt_pk_bf16_f32 v96, v92, v93
	v_cvt_pk_bf16_f32 v97, v94, v95
	v_cvt_pk_bf16_f32 v98, v88, v89
	v_cvt_pk_bf16_f32 v99, v90, v91
	global_store_dwordx4 v[214:215], v[96:99], off
	s_waitcnt vmcnt(13)
	v_pk_fma_f32 v[84:85], v[84:85], v[132:133], v[104:105]
	v_pk_fma_f32 v[86:87], v[86:87], v[134:135], v[106:107]
	v_pk_fma_f32 v[80:81], v[80:81], v[128:129], v[108:109]
	v_pk_fma_f32 v[82:83], v[82:83], v[130:131], v[110:111]
	v_cvt_pk_bf16_f32 v104, v84, v85
	v_cvt_pk_bf16_f32 v105, v86, v87
	v_cvt_pk_bf16_f32 v106, v80, v81
	v_cvt_pk_bf16_f32 v107, v82, v83
	global_store_dwordx4 v[214:215], v[104:107], off offset:256
	s_waitcnt vmcnt(12)
; DI unsigned cvt_pk_bf16(float lo, float hi) { unsigned r; asm volatile("v_cvt_pk_bf16_f32 %0, %1, %2" : "=v"(r) : "v"(lo), "v"(hi)); return r; }
;     DI void operator()(const f32x4 (&acc)[2][2][4][2], const Unit& u, int wr, int wc, int fr_, int fq_) const {
;     ...
;         } else {
; #pragma unroll
;             for (int ai = 0; ai < 2; ++ai)
; #pragma unroll
;                 for (int m = 0; m < 4; ++m) { const size_t off = roff + (size_t)(ai * HALF + wr * 64 + m * 16 + fr) * DM + col0;
; #pragma unroll
;                     for (int bj = 0; bj < 2; ++bj) { const int cc = bj * HALF;
;                         const f32x4 s0 = *(const f32x4*)((const float*)src + off + cc), s1 = *(const f32x4*)((const float*)src + off + cc + 4);
;                         const f32x4 o0 = s0 + gq[bj][0] * acc[ai][bj][m][0], o1 = s1 + gq[bj][1] * acc[ai][bj][m][1];
;                         if (db) { u32x4 o; o.x = cvt_pk_bf16(o0[0], o0[1]); o.y = cvt_pk_bf16(o0[2], o0[3]); o.z = cvt_pk_bf16(o1[0], o1[1]); o.w = cvt_pk_bf16(o1[2], o1[3]); *(u32x4*)((bf16_t*)dst + off + cc) = o; }
;                         else { *(f32x4*)((float*)dst + off + cc) = o0; *(f32x4*)((float*)dst + off + cc + 4) = o1; } }
;                     if (m & 1) asm volatile("" ::: "memory"); }
	v_pk_fma_f32 v[76:77], v[76:77], v[140:141], v[112:113]
	v_pk_fma_f32 v[78:79], v[78:79], v[142:143], v[114:115]
	v_pk_fma_f32 v[72:73], v[72:73], v[136:137], v[116:117]
	v_pk_fma_f32 v[74:75], v[74:75], v[138:139], v[118:119]
	v_cvt_pk_bf16_f32 v112, v76, v77
	v_cvt_pk_bf16_f32 v113, v78, v79
	v_cvt_pk_bf16_f32 v114, v72, v73
	v_cvt_pk_bf16_f32 v115, v74, v75
	global_store_dwordx4 v[218:219], v[112:115], off
	s_waitcnt vmcnt(11)
	v_pk_fma_f32 v[68:69], v[68:69], v[132:133], v[120:121]
	v_pk_fma_f32 v[70:71], v[70:71], v[134:135], v[122:123]
	v_pk_fma_f32 v[64:65], v[64:65], v[128:129], v[124:125]
	v_pk_fma_f32 v[66:67], v[66:67], v[130:131], v[126:127]
	v_cvt_pk_bf16_f32 v120, v68, v69
	v_cvt_pk_bf16_f32 v121, v70, v71
	v_cvt_pk_bf16_f32 v122, v64, v65
	v_cvt_pk_bf16_f32 v123, v66, v67
	global_store_dwordx4 v[218:219], v[120:123], off offset:256
	s_waitcnt vmcnt(10)
	v_pk_fma_f32 v[60:61], v[60:61], v[140:141], v[144:145]
	v_pk_fma_f32 v[62:63], v[62:63], v[142:143], v[146:147]
	v_pk_fma_f32 v[56:57], v[56:57], v[136:137], v[148:149]
	v_pk_fma_f32 v[58:59], v[58:59], v[138:139], v[150:151]
	v_cvt_pk_bf16_f32 v144, v60, v61
	v_cvt_pk_bf16_f32 v145, v62, v63
	v_cvt_pk_bf16_f32 v146, v56, v57
	v_cvt_pk_bf16_f32 v147, v58, v59
	global_store_dwordx4 v[228:229], v[144:147], off
	s_waitcnt vmcnt(9)
	v_pk_fma_f32 v[52:53], v[52:53], v[132:133], v[152:153]
	v_pk_fma_f32 v[54:55], v[54:55], v[134:135], v[154:155]
	v_pk_fma_f32 v[48:49], v[48:49], v[128:129], v[156:157]
	v_pk_fma_f32 v[50:51], v[50:51], v[130:131], v[158:159]
	v_cvt_pk_bf16_f32 v152, v52, v53
	v_cvt_pk_bf16_f32 v153, v54, v55
	v_cvt_pk_bf16_f32 v154, v48, v49
	v_cvt_pk_bf16_f32 v155, v50, v51
	global_store_dwordx4 v[228:229], v[152:155], off offset:256
	s_waitcnt vmcnt(8)
	v_pk_fma_f32 v[44:45], v[44:45], v[140:141], v[160:161]
	v_pk_fma_f32 v[46:47], v[46:47], v[142:143], v[162:163]
	v_pk_fma_f32 v[40:41], v[40:41], v[136:137], v[194:195]
	v_pk_fma_f32 v[42:43], v[42:43], v[138:139], v[196:197]
	v_cvt_pk_bf16_f32 v160, v44, v45
	v_cvt_pk_bf16_f32 v161, v46, v47
	v_cvt_pk_bf16_f32 v162, v40, v41
	v_cvt_pk_bf16_f32 v163, v42, v43
	global_store_dwordx4 v[232:233], v[160:163], off
	s_waitcnt vmcnt(7)
	v_pk_fma_f32 v[36:37], v[36:37], v[132:133], v[198:199]
	v_pk_fma_f32 v[38:39], v[38:39], v[134:135], v[200:201]
	v_pk_fma_f32 v[32:33], v[32:33], v[128:129], v[208:209]
	v_pk_fma_f32 v[34:35], v[34:35], v[130:131], v[210:211]
	v_cvt_pk_bf16_f32 v198, v36, v37
	v_cvt_pk_bf16_f32 v199, v38, v39
	v_cvt_pk_bf16_f32 v200, v32, v33
	v_cvt_pk_bf16_f32 v201, v34, v35
	global_store_dwordx4 v[232:233], v[198:201], off offset:256
	v_lshlrev_b64 v[220:221], 11, v[180:181]
	v_lshl_add_u64 v[220:221], v[174:175], 0, v[220:221]
	v_lshl_add_u64 v[212:213], v[220:221], 2, s[4:5]
	v_lshl_add_u64 v[214:215], v[220:221], 1, s[6:7]
	global_load_dwordx4 v[64:67], v[212:213], off
	global_load_dwordx4 v[68:71], v[212:213], off offset:16
	global_load_dwordx4 v[72:75], v[212:213], off offset:512
	global_load_dwordx4 v[76:79], v[212:213], off offset:528
	v_lshlrev_b64 v[220:221], 11, v[178:179]
	v_lshl_add_u64 v[220:221], v[174:175], 0, v[220:221]
	v_lshl_add_u64 v[216:217], v[220:221], 2, s[4:5]
	v_lshl_add_u64 v[218:219], v[220:221], 1, s[6:7]
	global_load_dwordx4 v[80:83], v[216:217], off
	global_load_dwordx4 v[84:87], v[216:217], off offset:16
	global_load_dwordx4 v[88:91], v[216:217], off offset:512
	global_load_dwordx4 v[92:95], v[216:217], off offset:528
	s_waitcnt vmcnt(6)
	v_pk_fma_f32 v[28:29], v[28:29], v[140:141], v[64:65]
	v_pk_fma_f32 v[30:31], v[30:31], v[142:143], v[66:67]
	v_pk_fma_f32 v[24:25], v[24:25], v[136:137], v[68:69]
	v_pk_fma_f32 v[26:27], v[26:27], v[138:139], v[70:71]
	v_cvt_pk_bf16_f32 v64, v28, v29
	v_cvt_pk_bf16_f32 v65, v30, v31
	v_cvt_pk_bf16_f32 v66, v24, v25
	v_cvt_pk_bf16_f32 v67, v26, v27
	global_store_dwordx4 v[214:215], v[64:67], off
	s_waitcnt vmcnt(5)
	v_pk_fma_f32 v[20:21], v[20:21], v[132:133], v[72:73]
	v_pk_fma_f32 v[22:23], v[22:23], v[134:135], v[74:75]
	v_pk_fma_f32 v[16:17], v[16:17], v[128:129], v[76:77]
	v_pk_fma_f32 v[18:19], v[18:19], v[130:131], v[78:79]
	v_cvt_pk_bf16_f32 v72, v20, v21
	v_cvt_pk_bf16_f32 v73, v22, v23
	v_cvt_pk_bf16_f32 v74, v16, v17
	v_cvt_pk_bf16_f32 v75, v18, v19
	global_store_dwordx4 v[214:215], v[72:75], off offset:256
	s_waitcnt vmcnt(4)
	v_pk_fma_f32 v[12:13], v[12:13], v[140:141], v[80:81]
	v_pk_fma_f32 v[14:15], v[14:15], v[142:143], v[82:83]
	v_pk_fma_f32 v[8:9], v[8:9], v[136:137], v[84:85]
	v_pk_fma_f32 v[10:11], v[10:11], v[138:139], v[86:87]
	v_cvt_pk_bf16_f32 v80, v12, v13
	v_cvt_pk_bf16_f32 v81, v14, v15
	v_cvt_pk_bf16_f32 v82, v8, v9
	v_cvt_pk_bf16_f32 v83, v10, v11
	global_store_dwordx4 v[218:219], v[80:83], off
	s_waitcnt vmcnt(3)
	v_pk_fma_f32 v[4:5], v[4:5], v[132:133], v[88:89]
	v_pk_fma_f32 v[6:7], v[6:7], v[134:135], v[90:91]
	v_pk_fma_f32 v[0:1], v[0:1], v[128:129], v[92:93]
	v_pk_fma_f32 v[2:3], v[2:3], v[130:131], v[94:95]
	v_cvt_pk_bf16_f32 v88, v4, v5
	v_cvt_pk_bf16_f32 v89, v6, v7
	v_cvt_pk_bf16_f32 v90, v0, v1
	v_cvt_pk_bf16_f32 v91, v2, v3
	global_store_dwordx4 v[218:219], v[88:91], off offset:256
	s_andn2_b64 vcc, exec, s[16:17]
	s_mov_b64 s[16:17], -1
	s_cbranch_vccnz .LBB0_734
